# attention near tiles: relative-bias lookups batched 8 at a time, one unsigned compare per element for validity
# speedup vs baseline: 1.0105x; 1.0073x over previous
; #define LAS __attribute__((address_space(3)))
; DEV void attn_tile(LAS unsigned char* lds, const bf16x8 (&qf)[2][2], int tl, int kpos0, int mode, bool near, bool rowsel, const float (&cbias)[2],
;                    unsigned kb, unsigned vb_, unsigned btb, int g4, float (&mrun)[2], float (&lrun)[2], f32x4 (&O)[2][4]) {
;     ...
;     if (near) {
; #pragma unroll
;         for (int kt = 0; kt < 4; ++kt)
; #pragma unroll
;             for (int r = 0; r < 4; ++r) { const int dist = tl - (kpos0 + kt * 16 + g4 * 4 + r);
;                 const bool valid = dist >= 0 && (mode == 1 ? rowsel : dist < 512);
;                 const int idx = dist < 0 ? 0 : (dist > 128 ? 128 : dist);
; #pragma unroll
;                 for (int hh = 0; hh < 2; ++hh) { const float s = sc[hh][kt][r] + *(const LAS float*)(lds + btb + idx * 4 + hh * 516); sc[hh][kt][r] = valid ? s : NEG_; } }
;     }
.LBB0_271:
	s_andn2_b64 vcc, exec, s[6:7]
	s_cbranch_vccnz .LBB0_273
	s_waitcnt lgkmcnt(0)
	v_lshl_or_b32 v153, s50, 6, v138
	v_bfrev_b32_e32 v159, 1
	v_sub_u32_e32 v153, v6, v153
	v_cndmask_b32_e64 v158, 0, v159, s[48:49]
	v_mov_b32_e32 v159, 0x200
	s_nop 0
	v_cndmask_b32_e64 v158, v159, v158, s[46:47]
	v_mov_b32_e32 v162, v153
	v_subrev_u32_e32 v163, 1, v153
	v_subrev_u32_e32 v164, 2, v153
	v_subrev_u32_e32 v165, 3, v153
	v_subrev_u32_e32 v166, 16, v153
	v_subrev_u32_e32 v167, 17, v153
	v_subrev_u32_e32 v168, 18, v153
	v_subrev_u32_e32 v169, 19, v153
	v_med3_i32 v180, v162, 0, v222
	v_med3_i32 v182, v163, 0, v222
	v_med3_i32 v184, v164, 0, v222
	v_med3_i32 v186, v165, 0, v222
	v_med3_i32 v188, v166, 0, v222
	v_med3_i32 v190, v167, 0, v222
	v_med3_i32 v154, v168, 0, v222
	v_med3_i32 v156, v169, 0, v222
	v_lshl_add_u32 v180, v180, 2, v142
	v_lshl_add_u32 v182, v182, 2, v142
	v_lshl_add_u32 v184, v184, 2, v142
	v_lshl_add_u32 v186, v186, 2, v142
	v_lshl_add_u32 v188, v188, 2, v142
	v_lshl_add_u32 v190, v190, 2, v142
	v_lshl_add_u32 v154, v154, 2, v142
	v_lshl_add_u32 v156, v156, 2, v142
	ds_read2_b32 v[180:181], v180 offset1:129
	ds_read2_b32 v[182:183], v182 offset1:129
	ds_read2_b32 v[184:185], v184 offset1:129
	ds_read2_b32 v[186:187], v186 offset1:129
	ds_read2_b32 v[188:189], v188 offset1:129
	ds_read2_b32 v[190:191], v190 offset1:129
	ds_read2_b32 v[154:155], v154 offset1:129
	ds_read2_b32 v[156:157], v156 offset1:129
	s_waitcnt lgkmcnt(0)
	v_cmp_lt_u32_e32 vcc, v162, v158
	v_add_f32_e32 v92, v92, v180
	v_add_f32_e32 v76, v76, v181
	v_cndmask_b32_e32 v92, v223, v92, vcc
	v_cndmask_b32_e32 v76, v223, v76, vcc
	v_cmp_lt_u32_e32 vcc, v163, v158
	v_add_f32_e32 v93, v93, v182
	v_add_f32_e32 v77, v77, v183
	v_cndmask_b32_e32 v93, v223, v93, vcc
	v_cndmask_b32_e32 v77, v223, v77, vcc
	v_cmp_lt_u32_e32 vcc, v164, v158
	v_add_f32_e32 v94, v94, v184
	v_add_f32_e32 v78, v78, v185
	v_cndmask_b32_e32 v94, v223, v94, vcc
	v_cndmask_b32_e32 v78, v223, v78, vcc
	v_cmp_lt_u32_e32 vcc, v165, v158
	v_add_f32_e32 v95, v95, v186
	v_add_f32_e32 v79, v79, v187
	v_cndmask_b32_e32 v95, v223, v95, vcc
	v_cndmask_b32_e32 v79, v223, v79, vcc
	v_cmp_lt_u32_e32 vcc, v166, v158
	v_add_f32_e32 v88, v88, v188
	v_add_f32_e32 v72, v72, v189
	v_cndmask_b32_e32 v88, v223, v88, vcc
	v_cndmask_b32_e32 v72, v223, v72, vcc
	v_cmp_lt_u32_e32 vcc, v167, v158
	v_add_f32_e32 v89, v89, v190
	v_add_f32_e32 v73, v73, v191
	v_cndmask_b32_e32 v89, v223, v89, vcc
	v_cndmask_b32_e32 v73, v223, v73, vcc
	v_cmp_lt_u32_e32 vcc, v168, v158
	v_add_f32_e32 v90, v90, v154
	v_add_f32_e32 v74, v74, v155
	v_cndmask_b32_e32 v90, v223, v90, vcc
	v_cndmask_b32_e32 v74, v223, v74, vcc
	v_cmp_lt_u32_e32 vcc, v169, v158
	v_add_f32_e32 v91, v91, v156
	v_add_f32_e32 v75, v75, v157
	v_cndmask_b32_e32 v91, v223, v91, vcc
	v_cndmask_b32_e32 v75, v223, v75, vcc
	v_subrev_u32_e32 v162, 32, v153
	v_subrev_u32_e32 v163, 33, v153
	v_subrev_u32_e32 v164, 34, v153
	v_subrev_u32_e32 v165, 35, v153
	v_subrev_u32_e32 v166, 48, v153
	v_subrev_u32_e32 v167, 49, v153
	v_subrev_u32_e32 v168, 50, v153
	v_subrev_u32_e32 v169, 51, v153
	v_med3_i32 v180, v162, 0, v222
	v_med3_i32 v182, v163, 0, v222
	v_med3_i32 v184, v164, 0, v222
	v_med3_i32 v186, v165, 0, v222
	v_med3_i32 v188, v166, 0, v222
	v_med3_i32 v190, v167, 0, v222
	v_med3_i32 v154, v168, 0, v222
	v_med3_i32 v156, v169, 0, v222
	v_lshl_add_u32 v180, v180, 2, v142
	v_lshl_add_u32 v182, v182, 2, v142
	v_lshl_add_u32 v184, v184, 2, v142
	v_lshl_add_u32 v186, v186, 2, v142
	v_lshl_add_u32 v188, v188, 2, v142
	v_lshl_add_u32 v190, v190, 2, v142
	v_lshl_add_u32 v154, v154, 2, v142
	v_lshl_add_u32 v156, v156, 2, v142
	ds_read2_b32 v[180:181], v180 offset1:129
	ds_read2_b32 v[182:183], v182 offset1:129
	ds_read2_b32 v[184:185], v184 offset1:129
	ds_read2_b32 v[186:187], v186 offset1:129
	ds_read2_b32 v[188:189], v188 offset1:129
	ds_read2_b32 v[190:191], v190 offset1:129
	ds_read2_b32 v[154:155], v154 offset1:129
	ds_read2_b32 v[156:157], v156 offset1:129
	s_waitcnt lgkmcnt(0)
	v_cmp_lt_u32_e32 vcc, v162, v158
	v_add_f32_e32 v84, v84, v180
	v_add_f32_e32 v64, v64, v181
	v_cndmask_b32_e32 v84, v223, v84, vcc
	v_cndmask_b32_e32 v64, v223, v64, vcc
	v_cmp_lt_u32_e32 vcc, v163, v158
	v_add_f32_e32 v85, v85, v182
	v_add_f32_e32 v65, v65, v183
	v_cndmask_b32_e32 v85, v223, v85, vcc
	v_cndmask_b32_e32 v65, v223, v65, vcc
	v_cmp_lt_u32_e32 vcc, v164, v158
	v_add_f32_e32 v86, v86, v184
	v_add_f32_e32 v66, v66, v185
	v_cndmask_b32_e32 v86, v223, v86, vcc
	v_cndmask_b32_e32 v66, v223, v66, vcc
	v_cmp_lt_u32_e32 vcc, v165, v158
	v_add_f32_e32 v87, v87, v186
	v_add_f32_e32 v67, v67, v187
	v_cndmask_b32_e32 v87, v223, v87, vcc
	v_cndmask_b32_e32 v67, v223, v67, vcc
	v_cmp_lt_u32_e32 vcc, v166, v158
	v_add_f32_e32 v80, v80, v188
	v_add_f32_e32 v68, v68, v189
	v_cndmask_b32_e32 v80, v223, v80, vcc
	v_cndmask_b32_e32 v68, v223, v68, vcc
	v_cmp_lt_u32_e32 vcc, v167, v158
	v_add_f32_e32 v81, v81, v190
	v_add_f32_e32 v69, v69, v191
	v_cndmask_b32_e32 v81, v223, v81, vcc
	v_cndmask_b32_e32 v69, v223, v69, vcc
	v_cmp_lt_u32_e32 vcc, v168, v158
	v_add_f32_e32 v82, v82, v154
	v_add_f32_e32 v70, v70, v155
	v_cndmask_b32_e32 v82, v223, v82, vcc
	v_cndmask_b32_e32 v70, v223, v70, vcc
	v_cmp_lt_u32_e32 vcc, v169, v158
	v_add_f32_e32 v83, v83, v156
	v_add_f32_e32 v71, v71, v157
	v_cndmask_b32_e32 v83, v223, v83, vcc
	v_cndmask_b32_e32 v71, v223, v71, vcc
